# FF1 start stagger skipped in the last layer, where the delayed workgroups have no slack
# speedup vs baseline: 1.0047x; 1.0047x over previous
.LBB0_642:
	s_cmp_lg_u32 s26, 3
	s_cbranch_scc1 .Lstag_next0
	s_cmpk_lt_u32 s53, 0x80
	s_cbranch_scc1 .Lstag_next0
	v_readlane_b32 s11, v244, 46
	s_nop 3
	s_cmp_eq_u32 s11, 4
	s_cbranch_scc1 .Lstag_next0
	s_sleep 127
	s_sleep 127
	s_sleep 127
